# FFN1 GEMM fully LDS-DMA staged (K-loop, tail, header, prologue); other GEMMs peeled DMA; fold batch; hdr relax
# speedup vs baseline: 1.0115x; 1.0115x over previous
.LBB0_132:
	s_andn2_b64 vcc, exec, s[28:29]
	s_cbranch_vccnz .LBB0_140
	v_readlane_b32 s0, v254, 41
	v_readlane_b32 s1, v254, 42
	s_mov_b64 s[28:29], 0
	v_mov_b32_e32 v80, v169
	s_andn2_b64 vcc, exec, s[0:1]
	s_cbranch_vccnz .LBB0_140
	s_add_u32 s28, s72, s28
	v_readlane_b32 s0, v255, 36
	s_addc_u32 s29, s73, s29
	v_readlane_b32 s1, v255, 37
	s_add_u32 s38, s28, 0x4991000
	s_mul_hi_i32 s1, s0, 0xb00000
	s_mul_i32 s0, s0, 0xb00000
	s_addc_u32 s39, s29, 0
	s_add_u32 s2, s28, s0
	s_addc_u32 s4, s29, s1
	v_mov_b32_e32 v0, v169
	s_add_u32 s42, s2, 0x1e80000
	s_load_dword s2, s[22:23], 0x0
	s_addc_u32 s43, s4, 0
	s_waitcnt vmcnt(7)
	v_lshrrev_b32_e32 v2, 3, v0
	v_readlane_b32 s4, v254, 43
	v_lshlrev_b32_e32 v0, 3, v0
	v_and_b32_e32 v0, 56, v0
	v_add_u32_e32 v2, s4, v2
	v_lshl_or_b32 v0, v2, 10, v0
	v_mov_b32_e32 v2, v169
	v_readlane_b32 s10, v254, 44
	v_lshrrev_b32_e32 v3, 3, v2
	v_lshlrev_b32_e32 v2, 3, v2
	v_add_u32_e32 v3, s10, v3
	v_and_b32_e32 v2, 56, v2
	v_lshl_or_b32 v72, v3, 10, v2
	s_waitcnt lgkmcnt(0)
	v_add_u32_e32 v66, 0x8000, v0
	v_add_u32_e32 v68, 0x10000, v0
	v_add_u32_e32 v70, 0x18000, v0
	v_add_u32_e32 v74, 0x8000, v72
	v_add_u32_e32 v76, 0x10000, v72
	v_add_u32_e32 v78, 0x18000, v72
	v_mov_b32_e32 v73, v1
	v_mov_b32_e32 v67, v1
	v_mov_b32_e32 v75, v1
	v_mov_b32_e32 v69, v1
	v_mov_b32_e32 v77, v1
	v_mov_b32_e32 v71, v1
	v_mov_b32_e32 v79, v1
	v_lshl_add_u64 v[2:3], v[0:1], 1, s[38:39]
	s_waitcnt vmcnt(6)
	v_lshl_add_u64 v[6:7], v[72:73], 1, s[42:43]
	s_waitcnt vmcnt(5)
	v_lshl_add_u64 v[10:11], v[66:67], 1, s[38:39]
	s_waitcnt vmcnt(4)
	v_lshl_add_u64 v[14:15], v[74:75], 1, s[42:43]
	s_waitcnt vmcnt(3)
	v_lshl_add_u64 v[18:19], v[68:69], 1, s[38:39]
	s_waitcnt vmcnt(2)
	v_lshl_add_u64 v[22:23], v[76:77], 1, s[42:43]
	s_waitcnt vmcnt(1)
	v_lshl_add_u64 v[26:27], v[70:71], 1, s[38:39]
	s_waitcnt vmcnt(0)
	v_lshl_add_u64 v[30:31], v[78:79], 1, s[42:43]
	v_lshrrev_b32_e32 v34, 6, v169
	v_lshlrev_b32_e32 v34, 10, v34
	s_nop 0
	v_readfirstlane_b32 s100, v34
	v_lshrrev_b32_e32 v35, 3, v169
	v_and_b32_e32 v36, 3, v35
	v_bfe_u32 v37, v35, 4, 1
	v_lshl_or_b32 v36, v37, 2, v36
	v_bfe_u32 v37, v35, 2, 1
	v_lshl_or_b32 v36, v37, 3, v36
	v_bfe_u32 v37, v35, 3, 1
	v_lshl_or_b32 v36, v37, 4, v36
	v_sub_u32_e32 v36, v36, v35
	v_lshlrev_b32_e32 v36, 11, v36
	v_and_b32_e32 v35, 7, v35
	v_lshlrev_b32_e32 v35, 4, v35
	v_ashrrev_i32_e32 v37, 31, v36
	v_xor_b32_e32 v2, v2, v35
	v_lshl_add_u64 v[6:7], v[6:7], 0, v[36:37]
	v_xor_b32_e32 v6, v6, v35
	v_xor_b32_e32 v10, v10, v35
	v_lshl_add_u64 v[14:15], v[14:15], 0, v[36:37]
	v_xor_b32_e32 v14, v14, v35
	v_xor_b32_e32 v18, v18, v35
	v_lshl_add_u64 v[22:23], v[22:23], 0, v[36:37]
	v_xor_b32_e32 v22, v22, v35
	v_xor_b32_e32 v26, v26, v35
	v_lshl_add_u64 v[30:31], v[30:31], 0, v[36:37]
	v_xor_b32_e32 v30, v30, v35
	s_add_u32 m0, s100, 0x0
	s_nop 0
	global_load_lds_dwordx4 v[2:3], off
	s_add_u32 m0, s100, 0x4000
	s_nop 0
	global_load_lds_dwordx4 v[6:7], off
	s_add_u32 m0, s100, 0x1000
	s_nop 0
	global_load_lds_dwordx4 v[10:11], off
	s_add_u32 m0, s100, 0x5000
	s_nop 0
	global_load_lds_dwordx4 v[14:15], off
	s_add_u32 m0, s100, 0x2000
	s_nop 0
	global_load_lds_dwordx4 v[18:19], off
	s_add_u32 m0, s100, 0x6000
	s_nop 0
	global_load_lds_dwordx4 v[22:23], off
	s_add_u32 m0, s100, 0x3000
	s_nop 0
	global_load_lds_dwordx4 v[26:27], off
	s_add_u32 m0, s100, 0x7000
	s_nop 0
	global_load_lds_dwordx4 v[30:31], off
	s_waitcnt vmcnt(0)
	v_and_b32_e32 v67, 15, v80
	v_ashrrev_i32_e32 v69, 1, v80
	s_movk_i32 s5, 0xffc0
	v_and_or_b32 v118, v69, s5, v67
	v_lshrrev_b32_e32 v67, 1, v80
	s_add_u32 s44, s28, 0xa991000
	v_and_b32_e32 v119, 64, v80
	v_and_b32_e32 v80, 24, v67
	s_addc_u32 s45, s29, 0
	s_waitcnt lgkmcnt(0)
	s_lshr_b32 s2, s2, 3
	v_or_b32_e32 v120, 16, v118
	v_or_b32_e32 v121, 32, v118
	v_or_b32_e32 v122, 48, v118
	v_lshlrev_b32_e32 v98, 1, v80
	v_readlane_b32 s9, v254, 57
	s_branch .LBB0_136

.LBB0_136:
	v_mov_b32_e32 v67, v169
	s_mov_b32 s8, s9
	v_lshrrev_b32_e32 v69, 4, v67
	v_ashrrev_i32_e32 v71, 3, v67
	v_lshrrev_b32_e32 v77, 1, v67
	v_and_b32_e32 v80, 4, v69
	v_and_b32_e32 v81, 3, v71
	v_and_b32_e32 v73, 7, v67
	v_xor_b32_e32 v75, v71, v67
	v_and_b32_e32 v77, 16, v77
	v_and_b32_e32 v79, 8, v69
	v_or_b32_e32 v82, v80, v81
	v_lshlrev_b32_e32 v75, 4, v75
	v_or3_b32 v77, v77, v79, v82
	v_bitop3_b32 v79, v80, v73, v81 bitop3:0x36
	v_lshlrev_b32_e32 v71, 7, v71
	v_lshlrev_b32_e32 v79, 4, v79
	v_and_or_b32 v123, v75, s24, v71
	v_lshl_or_b32 v99, v77, 7, v79
	v_lshlrev_b32_e32 v35, 7, v67
	v_bfe_u32 v34, v67, 4, 2
	v_and_b32_e32 v36, 0x780, v35
	v_and_b32_e32 v124, 0x2780, v35
	v_bitop3_b32 v35, v69, v73, 3 bitop3:0x6c
	v_mov_b32_e32 v75, v1
	v_lshlrev_b32_e32 v125, 4, v35
	v_lshlrev_b32_e32 v35, 6, v67
	v_bitop3_b32 v34, v34, v73, 4 bitop3:0x36
	v_mov_b32_e32 v73, v1
	v_mov_b32_e32 v67, v1
	v_mov_b32_e32 v69, v1
	v_mov_b32_e32 v77, v1
	v_mov_b32_e32 v71, v1
	v_mov_b32_e32 v79, v1
	v_lshl_add_u64 v[102:103], v[74:75], 1, s[0:1]
	v_mov_b32_e32 v74, 0
	s_mov_b32 s5, s10
	v_and_or_b32 v126, v35, s30, v36
	v_lshlrev_b32_e32 v127, 4, v34
	v_lshl_add_u64 v[100:101], v[72:73], 1, s[0:1]
	v_lshl_add_u64 v[104:105], v[76:77], 1, s[0:1]
	v_lshl_add_u64 v[106:107], v[78:79], 1, s[0:1]
	v_lshlrev_b64 v[108:109], 1, v[0:1]
	v_lshlrev_b64 v[110:111], 1, v[66:67]
	v_lshlrev_b64 v[112:113], 1, v[68:69]
	v_lshlrev_b64 v[114:115], 1, v[70:71]
	s_mov_b32 s9, -2
	s_mov_b64 s[46:47], s[28:29]
	v_mov_b32_e32 v75, v74
	v_mov_b32_e32 v76, v74
	v_mov_b32_e32 v77, v74
	v_mov_b32_e32 v62, v74
	v_mov_b32_e32 v63, v74
	v_mov_b32_e32 v64, v74
	v_mov_b32_e32 v65, v74
	v_mov_b32_e32 v66, v74
	v_mov_b32_e32 v67, v74
	v_mov_b32_e32 v68, v74
	v_mov_b32_e32 v69, v74
	v_mov_b32_e32 v58, v74
	v_mov_b32_e32 v59, v74
	v_mov_b32_e32 v60, v74
	v_mov_b32_e32 v61, v74
	v_mov_b32_e32 v70, v74
	v_mov_b32_e32 v71, v74
	v_mov_b32_e32 v72, v74
	v_mov_b32_e32 v73, v74
	v_mov_b32_e32 v54, v74
	v_mov_b32_e32 v55, v74
	v_mov_b32_e32 v56, v74
	v_mov_b32_e32 v57, v74
	v_mov_b32_e32 v78, v74
	v_mov_b32_e32 v79, v74
	v_mov_b32_e32 v80, v74
	v_mov_b32_e32 v81, v74
	v_mov_b32_e32 v50, v74
	v_mov_b32_e32 v51, v74
	v_mov_b32_e32 v52, v74
	v_mov_b32_e32 v53, v74
	v_mov_b32_e32 v82, v74
	v_mov_b32_e32 v83, v74
	v_mov_b32_e32 v84, v74
	v_mov_b32_e32 v85, v74
	v_mov_b32_e32 v46, v74
	v_mov_b32_e32 v47, v74
	v_mov_b32_e32 v48, v74
	v_mov_b32_e32 v49, v74
	v_mov_b32_e32 v86, v74
	v_mov_b32_e32 v87, v74
	v_mov_b32_e32 v88, v74
	v_mov_b32_e32 v89, v74
	v_mov_b32_e32 v42, v74
	v_mov_b32_e32 v43, v74
	v_mov_b32_e32 v44, v74
	v_mov_b32_e32 v45, v74
	v_mov_b32_e32 v90, v74
	v_mov_b32_e32 v91, v74
	v_mov_b32_e32 v92, v74
	v_mov_b32_e32 v93, v74
	v_mov_b32_e32 v38, v74
	v_mov_b32_e32 v39, v74
	v_mov_b32_e32 v40, v74
	v_mov_b32_e32 v41, v74
	v_mov_b32_e32 v94, v74
	v_mov_b32_e32 v95, v74
	v_mov_b32_e32 v96, v74
	v_mov_b32_e32 v97, v74
	v_mov_b32_e32 v34, v74
	v_mov_b32_e32 v35, v74
	v_mov_b32_e32 v36, v74
	v_mov_b32_e32 v37, v74
	s_waitcnt vmcnt(4)
	s_waitcnt lgkmcnt(0)
	s_barrier
	v_add_u32_e32 v128, v125, v124
	v_add_u32_e32 v130, v125, v126
	v_add_u32_e32 v129, v127, v126
	v_add_u32_e32 v131, v127, v124
	v_lshrrev_b32_e32 v218, 6, v169
	v_lshlrev_b32_e32 v218, 10, v218
	v_lshrrev_b32_e32 v219, 3, v169
	v_readfirstlane_b32 s100, v218
	v_and_b32_e32 v218, 3, v219
	v_bfe_u32 v220, v219, 4, 1
	v_lshl_or_b32 v218, v220, 2, v218
	v_bfe_u32 v220, v219, 2, 1
	v_lshl_or_b32 v218, v220, 3, v218
	v_bfe_u32 v220, v219, 3, 1
	v_lshl_or_b32 v218, v220, 4, v218
	v_sub_u32_e32 v218, v218, v219
	v_mul_i32_i24_e32 v218, 0x800, v218
	v_and_b32_e32 v219, 7, v219
	v_lshlrev_b32_e32 v219, 4, v219
	v_add_u32_e32 v206, 0x2b11000, v108
	v_xor_b32_e32 v194, v206, v219
	v_mov_b32_e32 v207, v100
	v_add_u32_e32 v195, v207, v218
	v_xor_b32_e32 v195, v195, v219
	v_add_u32_e32 v208, 0x2b11000, v110
	v_xor_b32_e32 v196, v208, v219
	v_mov_b32_e32 v209, v102
	v_add_u32_e32 v197, v209, v218
	v_xor_b32_e32 v197, v197, v219
	v_add_u32_e32 v214, 0x2b11000, v112
	v_xor_b32_e32 v202, v214, v219
	v_mov_b32_e32 v215, v104
	v_add_u32_e32 v203, v215, v218
	v_xor_b32_e32 v203, v203, v219
	v_add_u32_e32 v216, 0x2b11000, v114
	v_xor_b32_e32 v204, v216, v219
	v_mov_b32_e32 v217, v106
	v_add_u32_e32 v205, v217, v218
	v_xor_b32_e32 v205, v205, v219
.LBB0_137:
	s_setprio 1
	s_add_u32 s98, s46, s16
	s_addc_u32 s99, s47, 0
	s_add_u32 s98, s98, 0x80
	s_addc_u32 s99, s99, 0
	ds_read_b128 v[132:135], v128 offset:16384
	ds_read_b128 v[152:155], v128 offset:18432
	ds_read_b128 v[160:163], v128 offset:20480
	ds_read_b128 v[164:167], v128 offset:22528
	ds_read_b128 v[140:143], v130
	ds_read_b128 v[144:147], v130 offset:2048
	ds_read_b128 v[148:151], v130 offset:4096
	ds_read_b128 v[156:159], v130 offset:6144
	s_add_u32 m0, s100, 0x8000
	s_waitcnt lgkmcnt(3)
	v_mfma_f32_16x16x32_bf16 v[34:37], v[132:135], v[140:143], v[34:37]
	global_load_lds_dwordx4 v194, s[98:99]
	v_mfma_f32_16x16x32_bf16 v[94:97], v[152:155], v[140:143], v[94:97]
	ds_read_b128 v[198:201], v129
	s_add_u32 m0, s100, 0xc000
	v_mfma_f32_16x16x32_bf16 v[38:41], v[160:163], v[140:143], v[38:41]
	global_load_lds_dwordx4 v195, s[98:99]
	v_mfma_f32_16x16x32_bf16 v[90:93], v[164:167], v[140:143], v[90:93]
	ds_read_b128 v[140:143], v129 offset:2048
	s_add_u32 m0, s100, 0x9000
	s_waitcnt lgkmcnt(4)
	v_mfma_f32_16x16x32_bf16 v[42:45], v[132:135], v[144:147], v[42:45]
	global_load_lds_dwordx4 v196, s[98:99]
	v_mfma_f32_16x16x32_bf16 v[86:89], v[152:155], v[144:147], v[86:89]
	ds_read_b128 v[210:213], v129 offset:4096
	s_add_u32 m0, s100, 0xd000
	v_mfma_f32_16x16x32_bf16 v[46:49], v[160:163], v[144:147], v[46:49]
	global_load_lds_dwordx4 v197, s[98:99]
	v_mfma_f32_16x16x32_bf16 v[82:85], v[164:167], v[144:147], v[82:85]
	ds_read_b128 v[144:147], v129 offset:6144
	s_add_u32 m0, s100, 0xa000
	s_waitcnt lgkmcnt(5)
	v_mfma_f32_16x16x32_bf16 v[50:53], v[132:135], v[148:151], v[50:53]
	global_load_lds_dwordx4 v202, s[98:99]
	v_mfma_f32_16x16x32_bf16 v[78:81], v[152:155], v[148:151], v[78:81]
	ds_read_b128 v[222:225], v131 offset:16384
	s_add_u32 m0, s100, 0xe000
	v_mfma_f32_16x16x32_bf16 v[54:57], v[160:163], v[148:151], v[54:57]
	global_load_lds_dwordx4 v203, s[98:99]
	v_mfma_f32_16x16x32_bf16 v[70:73], v[164:167], v[148:151], v[70:73]
	ds_read_b128 v[148:151], v131 offset:18432
	s_add_u32 m0, s100, 0xb000
	s_waitcnt lgkmcnt(6)
	v_mfma_f32_16x16x32_bf16 v[58:61], v[132:135], v[156:159], v[58:61]
	global_load_lds_dwordx4 v204, s[98:99]
	v_mfma_f32_16x16x32_bf16 v[66:69], v[152:155], v[156:159], v[66:69]
	ds_read_b128 v[152:155], v131 offset:20480
	s_add_u32 m0, s100, 0xf000
	v_mfma_f32_16x16x32_bf16 v[62:65], v[160:163], v[156:159], v[62:65]
	global_load_lds_dwordx4 v205, s[98:99]
	v_mfma_f32_16x16x32_bf16 v[74:77], v[164:167], v[156:159], v[74:77]
	ds_read_b128 v[156:159], v131 offset:22528
	s_waitcnt lgkmcnt(3)
	v_mfma_f32_16x16x32_bf16 v[34:37], v[222:225], v[198:201], v[34:37]
	s_waitcnt lgkmcnt(2)
	v_mfma_f32_16x16x32_bf16 v[94:97], v[148:151], v[198:201], v[94:97]
	s_waitcnt lgkmcnt(1)
	v_mfma_f32_16x16x32_bf16 v[38:41], v[152:155], v[198:201], v[38:41]
	s_waitcnt lgkmcnt(0)
	v_mfma_f32_16x16x32_bf16 v[90:93], v[156:159], v[198:201], v[90:93]
	v_mfma_f32_16x16x32_bf16 v[42:45], v[222:225], v[140:143], v[42:45]
	v_mfma_f32_16x16x32_bf16 v[86:89], v[148:151], v[140:143], v[86:89]
	v_mfma_f32_16x16x32_bf16 v[46:49], v[152:155], v[140:143], v[46:49]
	v_mfma_f32_16x16x32_bf16 v[82:85], v[156:159], v[140:143], v[82:85]
	v_mfma_f32_16x16x32_bf16 v[50:53], v[222:225], v[210:213], v[50:53]
	v_mfma_f32_16x16x32_bf16 v[78:81], v[148:151], v[210:213], v[78:81]
	v_mfma_f32_16x16x32_bf16 v[54:57], v[152:155], v[210:213], v[54:57]
	v_mfma_f32_16x16x32_bf16 v[70:73], v[156:159], v[210:213], v[70:73]
	v_mfma_f32_16x16x32_bf16 v[58:61], v[222:225], v[144:147], v[58:61]
	v_mfma_f32_16x16x32_bf16 v[66:69], v[148:151], v[144:147], v[66:69]
	v_mfma_f32_16x16x32_bf16 v[62:65], v[152:155], v[144:147], v[62:65]
	v_mfma_f32_16x16x32_bf16 v[74:77], v[156:159], v[144:147], v[74:77]
	s_waitcnt vmcnt(0)
	s_setprio 0
	s_waitcnt lgkmcnt(0)
	s_barrier
	s_setprio 1
	s_add_u32 s98, s98, 0x80
	s_addc_u32 s99, s99, 0
	ds_read_b128 v[26:29], v128 offset:49152
	ds_read_b128 v[30:33], v128 offset:51200
	ds_read_b128 v[148:151], v128 offset:53248
	ds_read_b128 v[152:155], v128 offset:55296
	ds_read_b128 v[10:13], v130 offset:32768
	ds_read_b128 v[18:21], v130 offset:34816
	ds_read_b128 v[140:143], v130 offset:36864
	ds_read_b128 v[144:147], v130 offset:38912
	s_add_u32 m0, s100, 0x0
	s_waitcnt lgkmcnt(3)
	v_mfma_f32_16x16x32_bf16 v[34:37], v[26:29], v[10:13], v[34:37]
	global_load_lds_dwordx4 v194, s[98:99]
	v_mfma_f32_16x16x32_bf16 v[94:97], v[30:33], v[10:13], v[94:97]
	ds_read_b128 v[156:159], v129 offset:32768
	s_add_u32 m0, s100, 0x4000
	v_mfma_f32_16x16x32_bf16 v[38:41], v[148:151], v[10:13], v[38:41]
	global_load_lds_dwordx4 v195, s[98:99]
	v_mfma_f32_16x16x32_bf16 v[90:93], v[152:155], v[10:13], v[90:93]
	ds_read_b128 v[164:167], v129 offset:34816
	s_add_u32 m0, s100, 0x1000
	s_waitcnt lgkmcnt(4)
	v_mfma_f32_16x16x32_bf16 v[42:45], v[26:29], v[18:21], v[42:45]
	global_load_lds_dwordx4 v196, s[98:99]
	v_mfma_f32_16x16x32_bf16 v[86:89], v[30:33], v[18:21], v[86:89]
	ds_read_b128 v[198:201], v129 offset:36864
	s_add_u32 m0, s100, 0x5000
	v_mfma_f32_16x16x32_bf16 v[46:49], v[148:151], v[18:21], v[46:49]
	global_load_lds_dwordx4 v197, s[98:99]
	v_mfma_f32_16x16x32_bf16 v[82:85], v[152:155], v[18:21], v[82:85]
	ds_read_b128 v[210:213], v129 offset:38912
	s_add_u32 m0, s100, 0x2000
	s_waitcnt lgkmcnt(5)
	v_mfma_f32_16x16x32_bf16 v[50:53], v[26:29], v[140:143], v[50:53]
	global_load_lds_dwordx4 v202, s[98:99]
	v_mfma_f32_16x16x32_bf16 v[78:81], v[30:33], v[140:143], v[78:81]
	ds_read_b128 v[222:225], v131 offset:49152
	s_add_u32 m0, s100, 0x6000
	v_mfma_f32_16x16x32_bf16 v[54:57], v[148:151], v[140:143], v[54:57]
	global_load_lds_dwordx4 v203, s[98:99]
	v_mfma_f32_16x16x32_bf16 v[70:73], v[152:155], v[140:143], v[70:73]
	ds_read_b128 v[140:143], v131 offset:51200
	s_add_u32 m0, s100, 0x3000
	s_waitcnt lgkmcnt(6)
	v_mfma_f32_16x16x32_bf16 v[58:61], v[26:29], v[144:147], v[58:61]
	global_load_lds_dwordx4 v204, s[98:99]
	v_mfma_f32_16x16x32_bf16 v[66:69], v[30:33], v[144:147], v[66:69]
	ds_read_b128 v[230:233], v131 offset:53248
	s_add_u32 m0, s100, 0x7000
	v_mfma_f32_16x16x32_bf16 v[62:65], v[148:151], v[144:147], v[62:65]
	global_load_lds_dwordx4 v205, s[98:99]
	v_mfma_f32_16x16x32_bf16 v[74:77], v[152:155], v[144:147], v[74:77]
	ds_read_b128 v[144:147], v131 offset:55296
	s_waitcnt lgkmcnt(3)
	v_mfma_f32_16x16x32_bf16 v[34:37], v[222:225], v[156:159], v[34:37]
	s_waitcnt lgkmcnt(2)
	v_mfma_f32_16x16x32_bf16 v[94:97], v[140:143], v[156:159], v[94:97]
	s_waitcnt lgkmcnt(1)
	v_mfma_f32_16x16x32_bf16 v[38:41], v[230:233], v[156:159], v[38:41]
	s_waitcnt lgkmcnt(0)
	v_mfma_f32_16x16x32_bf16 v[90:93], v[144:147], v[156:159], v[90:93]
	v_mfma_f32_16x16x32_bf16 v[42:45], v[222:225], v[164:167], v[42:45]
	v_mfma_f32_16x16x32_bf16 v[86:89], v[140:143], v[164:167], v[86:89]
	v_mfma_f32_16x16x32_bf16 v[46:49], v[230:233], v[164:167], v[46:49]
	v_mfma_f32_16x16x32_bf16 v[82:85], v[144:147], v[164:167], v[82:85]
	v_mfma_f32_16x16x32_bf16 v[50:53], v[222:225], v[198:201], v[50:53]
	v_mfma_f32_16x16x32_bf16 v[78:81], v[140:143], v[198:201], v[78:81]
	v_mfma_f32_16x16x32_bf16 v[54:57], v[230:233], v[198:201], v[54:57]
	v_mfma_f32_16x16x32_bf16 v[70:73], v[144:147], v[198:201], v[70:73]
	v_mfma_f32_16x16x32_bf16 v[58:61], v[222:225], v[210:213], v[58:61]
	v_mfma_f32_16x16x32_bf16 v[66:69], v[140:143], v[210:213], v[66:69]
	v_mfma_f32_16x16x32_bf16 v[62:65], v[230:233], v[210:213], v[62:65]
	v_mfma_f32_16x16x32_bf16 v[74:77], v[144:147], v[210:213], v[74:77]
	s_waitcnt vmcnt(0)
	s_setprio 0
	s_add_i32 s9, s9, 2
	s_add_u32 s46, s46, 0x100
	s_addc_u32 s47, s47, 0
	s_cmp_lt_u32 s9, 12
	s_waitcnt lgkmcnt(0)
	s_barrier
	s_cbranch_scc1 .LBB0_137
	v_mov_b32_e32 v2, v194
	v_mov_b32_e32 v3, v195
	v_mov_b32_e32 v4, v196
	v_mov_b32_e32 v5, v197
	v_mov_b32_e32 v6, v202
	v_mov_b32_e32 v7, v203
	v_mov_b32_e32 v8, v204
	v_mov_b32_e32 v9, v205
	s_add_u32 s98, s46, s16
	s_addc_u32 s99, s47, 0
	s_add_u32 s98, s98, 0x80
	s_addc_u32 s99, s99, 0
	s_add_i32 s9, s8, s2
	s_cmpk_lt_u32 s9, 0x580
	s_cselect_b32 s8, s9, s8
	s_mul_hi_u32 s10, s8, 0xba2e8ba3
	s_lshr_b32 s10, s10, 8
	s_mul_i32 s11, s10, 0x160
	v_mov_b32_e32 v0, v169
	s_sub_i32 s11, s8, s11
	s_lshl_b32 s8, s10, 3
	s_add_i32 s8, s8, s21
	s_and_b32 s10, s11, 7
	v_lshlrev_b32_e32 v100, 3, v0
	v_lshlrev_b32_e32 v0, 7, v0
	s_or_b32 s8, s8, s10
	v_and_b32_e32 v0, 0xfffffc00, v0
	v_lshl_add_u32 v0, s8, 17, v0
	v_and_or_b32 v0, v100, 56, v0
	v_mov_b32_e32 v100, v169
	s_lshl_b32 s10, s11, 4
	s_and_b32 s10, s10, 0x1f80
	v_lshrrev_b32_e32 v101, 3, v100
	v_lshlrev_b32_e32 v100, 3, v100
	v_add_u32_e32 v101, s10, v101
	v_and_b32_e32 v100, 56, v100
	v_lshl_or_b32 v160, v101, 10, v100
	s_cmpk_gt_u32 s9, 0x57f
	s_cselect_b32 s101, 1, 0
	v_add_u32_e32 v116, 0x8000, v0
	v_add_u32_e32 v136, 0x10000, v0
	v_add_u32_e32 v174, 0x18000, v0
	v_add_u32_e32 v176, 0x8000, v160
	v_add_u32_e32 v178, 0x10000, v160
	v_add_u32_e32 v180, 0x18000, v160
	s_setprio 1
	ds_read_b128 v[100:103], v128 offset:16384
	ds_read_b128 v[112:115], v128 offset:18432
	ds_read_b128 v[140:143], v128 offset:20480
	ds_read_b128 v[144:147], v128 offset:22528
	ds_read_b128 v[104:107], v130
	ds_read_b128 v[108:111], v130 offset:2048
	ds_read_b128 v[124:127], v130 offset:4096
	ds_read_b128 v[132:135], v130 offset:6144
	v_lshrrev_b32_e32 v14, 3, v169
	v_and_b32_e32 v15, 3, v14
	v_bfe_u32 v16, v14, 4, 1
	v_lshl_or_b32 v15, v16, 2, v15
	v_bfe_u32 v16, v14, 2, 1
	v_lshl_or_b32 v15, v16, 3, v15
	v_bfe_u32 v16, v14, 3, 1
	v_lshl_or_b32 v15, v16, 4, v15
	v_sub_u32_e32 v15, v15, v14
	v_lshlrev_b32_e32 v15, 10, v15
	v_and_b32_e32 v14, 7, v14
	v_lshlrev_b32_e32 v14, 3, v14
	v_xor_b32_e32 v0, v0, v14
	v_add_u32_e32 v160, v160, v15
	v_xor_b32_e32 v160, v160, v14
	v_xor_b32_e32 v116, v116, v14
	v_add_u32_e32 v176, v176, v15
	v_xor_b32_e32 v176, v176, v14
	v_xor_b32_e32 v136, v136, v14
	v_add_u32_e32 v178, v178, v15
	v_xor_b32_e32 v178, v178, v14
	v_xor_b32_e32 v174, v174, v14
	v_add_u32_e32 v180, v180, v15
	v_xor_b32_e32 v180, v180, v14
	v_mov_b32_e32 v161, v1
	v_mov_b32_e32 v117, v1
	v_mov_b32_e32 v177, v1
	v_mov_b32_e32 v137, v1
	v_mov_b32_e32 v179, v1
	v_mov_b32_e32 v175, v1
	v_mov_b32_e32 v181, v1
	v_lshl_add_u64 v[186:187], v[0:1], 1, s[38:39]
	v_lshl_add_u64 v[188:189], v[160:161], 1, s[42:43]
	v_lshl_add_u64 v[116:117], v[116:117], 1, s[38:39]
	v_lshl_add_u64 v[176:177], v[176:177], 1, s[42:43]
	v_lshl_add_u64 v[136:137], v[136:137], 1, s[38:39]
	v_lshl_add_u64 v[178:179], v[178:179], 1, s[42:43]
	v_lshl_add_u64 v[174:175], v[174:175], 1, s[38:39]
	v_lshl_add_u64 v[180:181], v[180:181], 1, s[42:43]
	s_add_u32 m0, s100, 0x8000
	s_waitcnt lgkmcnt(3)
	v_mfma_f32_16x16x32_bf16 v[148:151], v[100:103], v[104:107], v[34:37]
	global_load_lds_dwordx4 v2, s[98:99]
	v_mfma_f32_16x16x32_bf16 v[94:97], v[112:115], v[104:107], v[94:97]
	ds_read_b128 v[152:155], v129
	s_add_u32 m0, s100, 0xc000
	v_mfma_f32_16x16x32_bf16 v[156:159], v[140:143], v[104:107], v[38:41]
	global_load_lds_dwordx4 v3, s[98:99]
	v_mfma_f32_16x16x32_bf16 v[90:93], v[144:147], v[104:107], v[90:93]
	ds_read_b128 v[104:107], v129 offset:2048
	s_add_u32 m0, s100, 0x9000
	s_waitcnt lgkmcnt(4)
	v_mfma_f32_16x16x32_bf16 v[160:163], v[100:103], v[108:111], v[42:45]
	global_load_lds_dwordx4 v4, s[98:99]
	v_mfma_f32_16x16x32_bf16 v[86:89], v[112:115], v[108:111], v[86:89]
	ds_read_b128 v[164:167], v129 offset:4096
	s_add_u32 m0, s100, 0xd000
	v_mfma_f32_16x16x32_bf16 v[194:197], v[140:143], v[108:111], v[46:49]
	global_load_lds_dwordx4 v5, s[98:99]
	v_mfma_f32_16x16x32_bf16 v[82:85], v[144:147], v[108:111], v[82:85]
	ds_read_b128 v[108:111], v129 offset:6144
	s_add_u32 m0, s100, 0xa000
	s_waitcnt lgkmcnt(5)
	v_mfma_f32_16x16x32_bf16 v[198:201], v[100:103], v[124:127], v[50:53]
	global_load_lds_dwordx4 v6, s[98:99]
	v_mfma_f32_16x16x32_bf16 v[78:81], v[112:115], v[124:127], v[78:81]
	ds_read_b128 v[202:205], v131 offset:16384
	s_add_u32 m0, s100, 0xe000
	v_mfma_f32_16x16x32_bf16 v[206:209], v[140:143], v[124:127], v[54:57]
	global_load_lds_dwordx4 v7, s[98:99]
	v_mfma_f32_16x16x32_bf16 v[70:73], v[144:147], v[124:127], v[70:73]
	ds_read_b128 v[124:127], v131 offset:18432
	s_add_u32 m0, s100, 0xb000
	s_waitcnt lgkmcnt(6)
	v_mfma_f32_16x16x32_bf16 v[100:103], v[100:103], v[132:135], v[58:61]
	global_load_lds_dwordx4 v8, s[98:99]
	v_mfma_f32_16x16x32_bf16 v[66:69], v[112:115], v[132:135], v[66:69]
	ds_read_b128 v[112:115], v131 offset:20480
	s_add_u32 m0, s100, 0xf000
	v_mfma_f32_16x16x32_bf16 v[140:143], v[140:143], v[132:135], v[62:65]
	global_load_lds_dwordx4 v9, s[98:99]
	v_mfma_f32_16x16x32_bf16 v[74:77], v[144:147], v[132:135], v[74:77]
	ds_read_b128 v[132:135], v131 offset:22528
	s_waitcnt lgkmcnt(3)
	v_mfma_f32_16x16x32_bf16 v[144:147], v[202:205], v[152:155], v[148:151]
	s_waitcnt lgkmcnt(2)
	v_mfma_f32_16x16x32_bf16 v[94:97], v[124:127], v[152:155], v[94:97]
	s_waitcnt lgkmcnt(1)
	v_mfma_f32_16x16x32_bf16 v[148:151], v[112:115], v[152:155], v[156:159]
	s_waitcnt lgkmcnt(0)
	v_mfma_f32_16x16x32_bf16 v[90:93], v[132:135], v[152:155], v[90:93]
	v_mfma_f32_16x16x32_bf16 v[152:155], v[202:205], v[104:107], v[160:163]
	v_mfma_f32_16x16x32_bf16 v[86:89], v[124:127], v[104:107], v[86:89]
	v_mfma_f32_16x16x32_bf16 v[156:159], v[112:115], v[104:107], v[194:197]
	v_mfma_f32_16x16x32_bf16 v[82:85], v[132:135], v[104:107], v[82:85]
	v_mfma_f32_16x16x32_bf16 v[104:107], v[202:205], v[164:167], v[198:201]
	v_mfma_f32_16x16x32_bf16 v[78:81], v[124:127], v[164:167], v[78:81]
	v_mfma_f32_16x16x32_bf16 v[160:163], v[112:115], v[164:167], v[206:209]
	v_mfma_f32_16x16x32_bf16 v[70:73], v[132:135], v[164:167], v[70:73]
	v_mfma_f32_16x16x32_bf16 v[100:103], v[202:205], v[108:111], v[100:103]
	v_mfma_f32_16x16x32_bf16 v[66:69], v[124:127], v[108:111], v[66:69]
	v_mfma_f32_16x16x32_bf16 v[112:115], v[112:115], v[108:111], v[140:143]
	v_mfma_f32_16x16x32_bf16 v[74:77], v[132:135], v[108:111], v[74:77]
	s_waitcnt vmcnt(0)
	s_setprio 0
	s_waitcnt lgkmcnt(0)
	s_barrier
	s_setprio 1
	ds_read_b128 v[26:29], v128 offset:49152
	ds_read_b128 v[30:33], v128 offset:51200
	ds_read_b128 v[132:135], v128 offset:53248
	ds_read_b128 v[140:143], v128 offset:55296
	ds_read_b128 v[10:13], v130 offset:32768
	ds_read_b128 v[18:21], v130 offset:34816
	ds_read_b128 v[108:111], v130 offset:36864
	ds_read_b128 v[124:127], v130 offset:38912
	s_add_u32 m0, s100, 0x0
	s_waitcnt lgkmcnt(3)
	v_mfma_f32_16x16x32_bf16 v[144:147], v[26:29], v[10:13], v[144:147]
	global_load_lds_dwordx4 v[186:187], off
	v_mfma_f32_16x16x32_bf16 v[94:97], v[30:33], v[10:13], v[94:97]
	ds_read_b128 v[164:167], v129 offset:32768
	s_add_u32 m0, s100, 0x4000
	v_mfma_f32_16x16x32_bf16 v[148:151], v[132:135], v[10:13], v[148:151]
	global_load_lds_dwordx4 v[188:189], off
	v_mfma_f32_16x16x32_bf16 v[90:93], v[140:143], v[10:13], v[90:93]
	ds_read_b128 v[194:197], v129 offset:34816
	s_add_u32 m0, s100, 0x1000
	s_waitcnt lgkmcnt(4)
	v_mfma_f32_16x16x32_bf16 v[152:155], v[26:29], v[18:21], v[152:155]
	global_load_lds_dwordx4 v[116:117], off
	v_mfma_f32_16x16x32_bf16 v[86:89], v[30:33], v[18:21], v[86:89]
	ds_read_b128 v[198:201], v129 offset:36864
	s_add_u32 m0, s100, 0x5000
	v_mfma_f32_16x16x32_bf16 v[156:159], v[132:135], v[18:21], v[156:159]
	global_load_lds_dwordx4 v[176:177], off
	v_mfma_f32_16x16x32_bf16 v[82:85], v[140:143], v[18:21], v[82:85]
	ds_read_b128 v[202:205], v129 offset:38912
	s_add_u32 m0, s100, 0x2000
	s_waitcnt lgkmcnt(5)
	v_mfma_f32_16x16x32_bf16 v[104:107], v[26:29], v[108:111], v[104:107]
	global_load_lds_dwordx4 v[136:137], off
	v_mfma_f32_16x16x32_bf16 v[78:81], v[30:33], v[108:111], v[78:81]
	ds_read_b128 v[206:209], v131 offset:49152
	s_add_u32 m0, s100, 0x6000
	v_mfma_f32_16x16x32_bf16 v[160:163], v[132:135], v[108:111], v[160:163]
	global_load_lds_dwordx4 v[178:179], off
	v_mfma_f32_16x16x32_bf16 v[70:73], v[140:143], v[108:111], v[70:73]
	ds_read_b128 v[108:111], v131 offset:51200
	s_add_u32 m0, s100, 0x3000
	s_waitcnt lgkmcnt(6)
	v_mfma_f32_16x16x32_bf16 v[100:103], v[26:29], v[124:127], v[100:103]
	global_load_lds_dwordx4 v[174:175], off
	v_mfma_f32_16x16x32_bf16 v[66:69], v[30:33], v[124:127], v[66:69]
	ds_read_b128 v[210:213], v131 offset:53248
	s_add_u32 m0, s100, 0x7000
	v_mfma_f32_16x16x32_bf16 v[112:115], v[132:135], v[124:127], v[112:115]
	global_load_lds_dwordx4 v[180:181], off
	v_mfma_f32_16x16x32_bf16 v[124:127], v[140:143], v[124:127], v[74:77]
	ds_read_b128 v[128:131], v131 offset:55296
	s_waitcnt lgkmcnt(3)
	v_mfma_f32_16x16x32_bf16 v[132:135], v[206:209], v[164:167], v[144:147]
	s_waitcnt lgkmcnt(2)
	v_mfma_f32_16x16x32_bf16 v[140:143], v[108:111], v[164:167], v[94:97]
	s_waitcnt lgkmcnt(1)
	v_mfma_f32_16x16x32_bf16 v[144:147], v[210:213], v[164:167], v[148:151]
	s_waitcnt lgkmcnt(0)
	v_mfma_f32_16x16x32_bf16 v[148:151], v[128:131], v[164:167], v[90:93]
	v_mfma_f32_16x16x32_bf16 v[152:155], v[206:209], v[194:197], v[152:155]
	v_mfma_f32_16x16x32_bf16 v[164:167], v[108:111], v[194:197], v[86:89]
	v_mfma_f32_16x16x32_bf16 v[156:159], v[210:213], v[194:197], v[156:159]
	v_mfma_f32_16x16x32_bf16 v[194:197], v[128:131], v[194:197], v[82:85]
	v_mfma_f32_16x16x32_bf16 v[94:97], v[206:209], v[198:201], v[104:107]
	v_mfma_f32_16x16x32_bf16 v[86:89], v[108:111], v[198:201], v[78:81]
	v_mfma_f32_16x16x32_bf16 v[90:93], v[210:213], v[198:201], v[160:163]
	v_mfma_f32_16x16x32_bf16 v[82:85], v[128:131], v[198:201], v[70:73]
	v_mfma_f32_16x16x32_bf16 v[74:77], v[206:209], v[202:205], v[100:103]
	v_mfma_f32_16x16x32_bf16 v[66:69], v[108:111], v[202:205], v[66:69]
	v_mfma_f32_16x16x32_bf16 v[70:73], v[210:213], v[202:205], v[112:115]
	v_mfma_f32_16x16x32_bf16 v[78:81], v[128:131], v[202:205], v[124:127]
	s_setprio 0
	v_mul_f32_e32 v0, 0xbfb8aa3b, v132
	v_exp_f32_e32 v0, v0
	v_mul_f32_e32 v99, 0xbfb8aa3b, v133
	v_exp_f32_e32 v99, v99
	v_mul_f32_e32 v101, 0xbfb8aa3b, v135
	v_add_f32_e32 v0, 1.0, v0
	v_rcp_f32_e32 v100, v0
	v_add_f32_e32 v0, 1.0, v99
	v_mul_f32_e32 v99, 0xbfb8aa3b, v134
	v_exp_f32_e32 v99, v99
	v_exp_f32_e32 v103, v101
	v_rcp_f32_e32 v101, v0
	v_mul_f32_e32 v108, 0xbfb8aa3b, v152
	v_add_f32_e32 v0, 1.0, v99
	v_mul_f32_e32 v99, 0xbfb8aa3b, v140
	v_rcp_f32_e32 v102, v0
	v_add_f32_e32 v0, 1.0, v103
	v_exp_f32_e32 v99, v99
	v_mul_f32_e32 v103, 0xbfb8aa3b, v141
	v_exp_f32_e32 v105, v103
	v_rcp_f32_e32 v103, v0
	v_add_f32_e32 v0, 1.0, v99
	v_mul_f32_e32 v99, 0xbfb8aa3b, v142
	v_rcp_f32_e32 v104, v0
	v_add_f32_e32 v0, 1.0, v105
	v_exp_f32_e32 v99, v99
	v_mul_f32_e32 v105, 0xbfb8aa3b, v143
	v_exp_f32_e32 v107, v105
	v_rcp_f32_e32 v105, v0
	v_add_f32_e32 v0, 1.0, v99
	v_rcp_f32_e32 v106, v0
	v_add_f32_e32 v0, 1.0, v107
	v_rcp_f32_e32 v107, v0
	v_pk_mul_f32 v[100:101], v[132:133], v[100:101]
	v_pk_mul_f32 v[102:103], v[134:135], v[102:103]
	v_pk_mul_f32 v[100:101], v[144:145], v[100:101]
	v_pk_mul_f32 v[102:103], v[146:147], v[102:103]
	v_cvt_pk_bf16_f32 v100, v100, v101
	v_cvt_pk_bf16_f32 v101, v102, v103
	v_pk_mul_f32 v[102:103], v[140:141], v[104:105]
	v_pk_mul_f32 v[104:105], v[142:143], v[106:107]
	v_pk_mul_f32 v[102:103], v[148:149], v[102:103]
	v_pk_mul_f32 v[104:105], v[150:151], v[104:105]
	v_add_u32_e32 v0, s4, v118
	v_cvt_pk_bf16_f32 v102, v102, v103
	v_cvt_pk_bf16_f32 v103, v104, v105
	v_mov_b64_e32 v[104:105], s[44:45]
	v_mad_i64_i32 v[106:107], s[14:15], v0, s20, v[104:105]
	v_or_b32_e32 v0, s5, v119
	v_mul_f32_e32 v109, 0xbfb8aa3b, v153
	v_lshl_add_u64 v[106:107], v[106:107], 0, v[0:1]
	v_mov_b32_e32 v99, v1
	v_exp_f32_e32 v108, v108
	v_exp_f32_e32 v109, v109
	v_lshl_add_u64 v[106:107], v[106:107], 0, v[98:99]
	s_barrier
	global_store_dwordx4 v[106:107], v[100:103], off
	v_mul_f32_e32 v106, 0xbfb8aa3b, v164
	v_mul_f32_e32 v107, 0xbfb8aa3b, v165
	v_mul_f32_e32 v102, 0xbfb8aa3b, v154
	v_mul_f32_e32 v103, 0xbfb8aa3b, v155
	v_exp_f32_e32 v102, v102
	v_exp_f32_e32 v103, v103
	v_add_f32_e32 v100, 1.0, v108
	v_add_f32_e32 v101, 1.0, v109
	v_mul_f32_e32 v108, 0xbfb8aa3b, v166
	v_mul_f32_e32 v109, 0xbfb8aa3b, v167
	v_exp_f32_e32 v106, v106
	v_exp_f32_e32 v107, v107
	v_exp_f32_e32 v108, v108
	v_exp_f32_e32 v109, v109
	v_add_f32_e32 v102, 1.0, v102
	v_add_f32_e32 v103, 1.0, v103
	v_rcp_f32_e32 v100, v100
	v_rcp_f32_e32 v101, v101
	v_rcp_f32_e32 v102, v102
	v_rcp_f32_e32 v103, v103
	v_add_f32_e32 v106, 1.0, v106
	v_add_f32_e32 v107, 1.0, v107
	v_add_f32_e32 v108, 1.0, v108
	v_add_f32_e32 v109, 1.0, v109
	v_rcp_f32_e32 v106, v106
	v_rcp_f32_e32 v107, v107
	v_rcp_f32_e32 v108, v108
	v_rcp_f32_e32 v109, v109
	v_pk_mul_f32 v[100:101], v[152:153], v[100:101]
	v_pk_mul_f32 v[102:103], v[154:155], v[102:103]
	v_pk_mul_f32 v[100:101], v[156:157], v[100:101]
	v_pk_mul_f32 v[102:103], v[158:159], v[102:103]
	v_cvt_pk_bf16_f32 v100, v100, v101
	v_cvt_pk_bf16_f32 v101, v102, v103
	v_pk_mul_f32 v[102:103], v[164:165], v[106:107]
	v_pk_mul_f32 v[106:107], v[166:167], v[108:109]
	v_add_u32_e32 v110, s4, v120
	v_pk_mul_f32 v[102:103], v[194:195], v[102:103]
	v_pk_mul_f32 v[106:107], v[196:197], v[106:107]
	v_cvt_pk_bf16_f32 v102, v102, v103
	v_cvt_pk_bf16_f32 v103, v106, v107
	v_mad_i64_i32 v[106:107], s[14:15], v110, s20, v[104:105]
	v_mul_f32_e32 v108, 0xbfb8aa3b, v94
	v_mul_f32_e32 v109, 0xbfb8aa3b, v95
	v_lshl_add_u64 v[106:107], v[106:107], 0, v[0:1]
	v_exp_f32_e32 v108, v108
	v_exp_f32_e32 v109, v109
	v_lshl_add_u64 v[106:107], v[106:107], 0, v[98:99]
	global_store_dwordx4 v[106:107], v[100:103], off
	v_mul_f32_e32 v106, 0xbfb8aa3b, v86
	v_mul_f32_e32 v107, 0xbfb8aa3b, v87
	v_mul_f32_e32 v102, 0xbfb8aa3b, v96
	v_mul_f32_e32 v103, 0xbfb8aa3b, v97
	v_exp_f32_e32 v102, v102
	v_exp_f32_e32 v103, v103
	v_exp_f32_e32 v106, v106
	v_exp_f32_e32 v107, v107
	v_add_f32_e32 v100, 1.0, v108
	v_add_f32_e32 v101, 1.0, v109
	v_mul_f32_e32 v108, 0xbfb8aa3b, v88
	v_mul_f32_e32 v109, 0xbfb8aa3b, v89
	v_exp_f32_e32 v108, v108
	v_exp_f32_e32 v109, v109
	v_rcp_f32_e32 v100, v100
	v_rcp_f32_e32 v101, v101
	v_add_f32_e32 v102, 1.0, v102
	v_add_f32_e32 v103, 1.0, v103
	v_add_f32_e32 v106, 1.0, v106
	v_add_f32_e32 v107, 1.0, v107
	v_rcp_f32_e32 v102, v102
	v_rcp_f32_e32 v103, v103
	v_rcp_f32_e32 v106, v106
	v_rcp_f32_e32 v107, v107
	v_add_f32_e32 v108, 1.0, v108
	v_add_f32_e32 v109, 1.0, v109
	v_rcp_f32_e32 v108, v108
	v_rcp_f32_e32 v109, v109
	v_pk_mul_f32 v[94:95], v[94:95], v[100:101]
	v_pk_mul_f32 v[86:87], v[86:87], v[106:107]
	v_pk_mul_f32 v[90:91], v[90:91], v[94:95]
	v_pk_mul_f32 v[94:95], v[96:97], v[102:103]
	v_pk_mul_f32 v[82:83], v[82:83], v[86:87]
	v_pk_mul_f32 v[92:93], v[92:93], v[94:95]
	v_cvt_pk_bf16_f32 v90, v90, v91
	v_cvt_pk_bf16_f32 v91, v92, v93
	v_cvt_pk_bf16_f32 v92, v82, v83
	v_pk_mul_f32 v[82:83], v[88:89], v[108:109]
	v_add_u32_e32 v110, s4, v121
	v_pk_mul_f32 v[82:83], v[84:85], v[82:83]
	v_mul_f32_e32 v84, 0xbfb8aa3b, v74
	v_mul_f32_e32 v85, 0xbfb8aa3b, v75
	v_exp_f32_e32 v84, v84
	v_exp_f32_e32 v85, v85
	v_cvt_pk_bf16_f32 v93, v82, v83
	v_mad_i64_i32 v[82:83], s[14:15], v110, s20, v[104:105]
	v_lshl_add_u64 v[82:83], v[82:83], 0, v[0:1]
	v_lshl_add_u64 v[82:83], v[82:83], 0, v[98:99]
	global_store_dwordx4 v[82:83], v[90:93], off
	v_add_f32_e32 v82, 1.0, v84
	v_add_f32_e32 v83, 1.0, v85
	v_mul_f32_e32 v84, 0xbfb8aa3b, v76
	v_mul_f32_e32 v85, 0xbfb8aa3b, v77
	v_mul_f32_e32 v86, 0xbfb8aa3b, v66
	v_mul_f32_e32 v87, 0xbfb8aa3b, v67
	v_exp_f32_e32 v84, v84
	v_exp_f32_e32 v85, v85
	v_exp_f32_e32 v86, v86
	v_exp_f32_e32 v87, v87
	v_mul_f32_e32 v88, 0xbfb8aa3b, v68
	v_mul_f32_e32 v89, 0xbfb8aa3b, v69
	v_exp_f32_e32 v88, v88
	v_exp_f32_e32 v89, v89
	v_rcp_f32_e32 v82, v82
	v_rcp_f32_e32 v83, v83
	v_add_f32_e32 v84, 1.0, v84
	v_add_f32_e32 v85, 1.0, v85
	v_add_f32_e32 v86, 1.0, v86
	v_add_f32_e32 v87, 1.0, v87
	v_rcp_f32_e32 v84, v84
	v_rcp_f32_e32 v85, v85
	v_rcp_f32_e32 v86, v86
	v_rcp_f32_e32 v87, v87
	v_add_f32_e32 v88, 1.0, v88
	v_add_f32_e32 v89, 1.0, v89
	v_rcp_f32_e32 v88, v88
	v_rcp_f32_e32 v89, v89
	v_pk_mul_f32 v[74:75], v[74:75], v[82:83]
	v_pk_mul_f32 v[66:67], v[66:67], v[86:87]
	v_pk_mul_f32 v[70:71], v[70:71], v[74:75]
	v_pk_mul_f32 v[74:75], v[76:77], v[84:85]
	v_pk_mul_f32 v[66:67], v[78:79], v[66:67]
	v_pk_mul_f32 v[72:73], v[72:73], v[74:75]
	v_cvt_pk_bf16_f32 v70, v70, v71
	v_cvt_pk_bf16_f32 v71, v72, v73
	v_cvt_pk_bf16_f32 v72, v66, v67
	v_pk_mul_f32 v[66:67], v[68:69], v[88:89]
	v_add_u32_e32 v90, s4, v122
	v_pk_mul_f32 v[66:67], v[80:81], v[66:67]
	s_nop 0
	v_cvt_pk_bf16_f32 v73, v66, v67
	v_mad_i64_i32 v[66:67], s[4:5], v90, s20, v[104:105]
	v_lshl_add_u64 v[66:67], v[66:67], 0, v[0:1]
	v_lshl_add_u64 v[66:67], v[66:67], 0, v[98:99]
	global_store_dwordx4 v[66:67], v[70:73], off
	s_cmp_lg_u32 s101, 0
	s_cbranch_scc0 .LBB0_135
